# prompt-attention loop in ping-pong form (SIMD partner waves alternate LOAD/COMPUTE segments, 2 barriers per KV tile) with softmax VALU spread to <=24 issue cycles per MFMA gap
# speedup vs baseline: 1.0113x; 1.0113x over previous
; DI void attn_unit(const Params& p, LAS unsigned char* ldsu, int kind, int b, int h, int u, float lam) {
;     ...
;     f32x16 O[4]; float l = 0.f;
; #pragma unroll
;     for (int v = 0; v < 4; ++v)
; #pragma unroll
;         for (int i = 0; i < 16; ++i) O[v][i] = 0.f;
;     const int i16 = lane & 15, q4 = i16 >> 2, p4 = i16 & 3, blk = (lane >> 4) & 1;
;     const int kboff = qr * KRS + 16 * hh + cmp * 128, vboff = SLOT_V + (4 * hh + q4) * VRS + blk * 32 + p4 * 8;
;     ...
;     if (kind == 0) {
;         unsigned poff[5]; dma_offsets(poff, wid, lane);
;         auto stage = [&](int t) { if (t >= ntl) t = ntl - 1; const int row0 = t == 0 ? ROW_M : b * SEQ + (t - 1) * 64;
;             dma_tile(lds + (t & 3) * SLOT_B, KB + (size_t)row0 * 512 + hc, VB + (size_t)row0 * 512 + hc, poff, wid); };
;         stage(0); stage(1); stage(2);
;         asm volatile("s_waitcnt vmcnt(10)" ::: "memory");
;         __syncthreads();
;         for (int t = 0; t < ntl; ++t) {
;             stage(t + 3);
.LBB0_743:
	s_add_i32 s6, s31, -1
	v_readlane_b32 s7, v254, 22
	s_add_u32 s22, s7, s62
	v_readlane_b32 s7, v254, 23
	s_addc_u32 s23, s7, 0
	v_readlane_b32 s7, v254, 24
	s_add_u32 s24, s7, s62
	v_readlane_b32 s7, v254, 25
	s_addc_u32 s25, s7, 0
	s_and_b64 s[10:11], s[0:1], exec
	v_lshlrev_b32_e32 v0, 10, v0
	v_min_i32_e32 v2, 15, v2
	s_cselect_b32 s21, s23, s25
	s_cselect_b32 s20, s22, s24
	s_lshl_b32 s7, s12, 10
	v_lshl_or_b32 v132, v2, 4, v0
	s_add_i32 s26, s7, 0
	s_mov_b32 s10, m0
	s_mov_b32 m0, s26
	s_nop 0
	global_load_lds_dwordx4 v132, s[20:21]
	s_mov_b32 m0, s10
	s_lshl_b32 s10, s13, 10
	s_add_i32 s27, s10, 0
	s_add_i32 s11, s27, 0x400
	v_lshlrev_b32_e32 v3, 10, v3
	v_min_i32_e32 v4, 15, v4
	s_and_b64 s[12:13], exec, s[8:9]
	v_lshl_or_b32 v131, v4, 4, v3
	s_mov_b32 s12, m0
	s_mov_b32 m0, s11
	s_nop 0
	global_load_lds_dwordx4 v131, s[20:21]
	s_mov_b32 m0, s12
	s_cselect_b32 s21, s23, s25
	s_cselect_b32 s20, s22, s24
	s_lshl_b32 s11, s18, 10
	s_add_i32 s22, s11, 0
	v_lshlrev_b32_e32 v5, 10, v5
	v_min_i32_e32 v6, 15, v6
	s_add_i32 s12, s22, 0x800
	v_lshl_or_b32 v130, v6, 4, v5
	s_mov_b32 s13, m0
	s_mov_b32 m0, s12
	s_nop 0
	global_load_lds_dwordx4 v130, s[20:21]
	s_mov_b32 m0, s13
	s_lshl_b32 s12, s19, 10
	s_add_i32 s23, s12, 0
	v_lshlrev_b32_e32 v7, 10, v7
	v_min_i32_e32 v8, 15, v8
	s_add_i32 s13, s23, 0xc00
	v_lshl_or_b32 v129, v8, 4, v7
	s_mov_b32 s18, m0
	s_mov_b32 m0, s13
	s_nop 0
	global_load_lds_dwordx4 v129, s[20:21]
	s_mov_b32 m0, s18
	s_lshl_b32 s13, s17, 10
	s_add_i32 s24, s13, 0
	v_lshlrev_b32_e32 v0, 10, v9
	v_min_i32_e32 v2, 15, v10
	s_add_i32 s17, s24, 0x1000
	v_lshl_or_b32 v133, v2, 4, v0
	s_mov_b32 s18, m0
	s_mov_b32 m0, s17
	s_nop 0
	global_load_lds_dwordx4 v133, s[20:21]
	s_mov_b32 m0, s18
	s_lshl_b32 s17, s16, 12
	s_sub_i32 s17, s17, 64
	s_lshl_b32 s16, s16, 22
	v_readlane_b32 s36, v254, 14
	s_add_u32 s18, s36, s16
	v_readlane_b32 s37, v254, 15
	s_addc_u32 s19, s37, 0
	s_add_u32 s20, s18, s62
	s_addc_u32 s21, s19, 0
	v_readlane_b32 s38, v254, 16
	s_add_u32 s18, s38, s16
	v_readlane_b32 s39, v254, 17
	s_addc_u32 s19, s39, 0
	s_add_u32 s25, s18, s62
	s_addc_u32 s34, s19, 0
	s_and_b64 s[18:19], s[0:1], exec
	s_cselect_b32 s19, s21, s34
	s_cselect_b32 s18, s20, s25
	s_add_i32 s26, s26, 0x9400
	s_mov_b32 s35, m0
	s_mov_b32 m0, s26
	s_nop 0
	global_load_lds_dwordx4 v132, s[18:19]
	s_mov_b32 m0, s35
	s_add_i32 s27, s27, 0x9800
	s_mov_b32 s26, m0
	s_mov_b32 m0, s27
	s_nop 0
	global_load_lds_dwordx4 v131, s[18:19]
	s_mov_b32 m0, s26
	s_and_b64 s[18:19], exec, s[8:9]
	s_cselect_b32 s19, s21, s34
	s_cselect_b32 s18, s20, s25
	s_add_i32 s22, s22, 0x9c00
	s_mov_b32 s20, m0
	s_mov_b32 m0, s22
	s_nop 0
	global_load_lds_dwordx4 v130, s[18:19]
	s_mov_b32 m0, s20
	s_add_i32 s23, s23, 0xa000
	s_mov_b32 s20, m0
	s_mov_b32 m0, s23
	s_nop 0
	global_load_lds_dwordx4 v129, s[18:19]
	s_mov_b32 m0, s20
	s_add_i32 s24, s24, 0xa400
	s_bitset1_b32 s16, 16
	s_mov_b32 s20, m0
	s_mov_b32 m0, s24
	s_nop 0
	global_load_lds_dwordx4 v133, s[18:19]
	s_mov_b32 m0, s20
	s_add_u32 s18, s36, s16
	s_addc_u32 s19, s37, 0
	s_add_u32 s20, s18, s62
	s_addc_u32 s21, s19, 0
	s_add_u32 s16, s38, s16
	s_addc_u32 s18, s39, 0
	s_add_u32 s16, s16, s62
	s_addc_u32 s22, s18, 0
	s_and_b64 s[18:19], s[0:1], exec
	v_readlane_b32 s25, v254, 30
	s_cselect_b32 s19, s21, s22
	s_cselect_b32 s18, s20, s16
	s_add_i32 s23, s25, s7
	s_mov_b32 s24, m0
	s_mov_b32 m0, s23
	s_nop 0
	global_load_lds_dwordx4 v132, s[18:19]
	s_mov_b32 m0, s24
	s_add_i32 s23, s25, s10
	s_addk_i32 s23, 0x400
	s_mov_b32 s24, m0
	s_mov_b32 m0, s23
	s_nop 0
	global_load_lds_dwordx4 v131, s[18:19]
	s_mov_b32 m0, s24
	s_and_b64 s[18:19], exec, s[8:9]
	s_cselect_b32 s19, s21, s22
	s_cselect_b32 s18, s20, s16
	s_add_i32 s16, s25, s11
	s_addk_i32 s16, 0x800
	s_mov_b32 s20, m0
	s_mov_b32 m0, s16
	s_nop 0
	global_load_lds_dwordx4 v130, s[18:19]
	s_mov_b32 m0, s20
	s_add_i32 s16, s25, s12
	s_addk_i32 s16, 0xc00
	s_mov_b32 s20, m0
	s_mov_b32 m0, s16
	s_nop 0
	global_load_lds_dwordx4 v129, s[18:19]
	s_mov_b32 m0, s20
	s_add_i32 s16, s25, s13
	s_addk_i32 s16, 0x1000
	s_mov_b32 s20, m0
	s_mov_b32 m0, s16
	s_nop 0
	global_load_lds_dwordx4 v133, s[18:19]
	s_mov_b32 m0, s20
	s_add_u32 s16, s36, s62
	s_waitcnt vmcnt(10)
	s_addc_u32 s18, s37, 0
	v_mov_b32_e32 v14, v1
	v_mov_b32_e32 v15, v1
	s_add_u32 s19, s38, s62
	v_mov_b32_e32 v0, v1
	v_mov_b32_e32 v2, v1
	v_mov_b32_e32 v3, v1
	v_mov_b32_e32 v4, v1
	v_mov_b32_e32 v5, v1
	v_mov_b32_e32 v6, v1
	v_mov_b32_e32 v7, v1
	v_mov_b32_e32 v8, v1
	v_mov_b32_e32 v9, v1
	v_mov_b32_e32 v10, v1
	v_mov_b32_e32 v11, v1
	v_mov_b32_e32 v12, v1
	v_mov_b32_e32 v13, v1
	v_mov_b64_e32 v[30:31], v[14:15]
	v_mov_b64_e32 v[46:47], v[14:15]
	v_mov_b64_e32 v[62:63], v[14:15]
	v_mov_b64_e32 v[78:79], v[14:15]
	s_addc_u32 s20, s39, 0
	v_add3_u32 v134, v176, v177, v178
	s_mov_b32 s21, 0
	v_mov_b32_e32 v175, 0
	v_mov_b64_e32 v[28:29], v[12:13]
	v_mov_b64_e32 v[26:27], v[10:11]
	v_mov_b64_e32 v[24:25], v[8:9]
	v_mov_b64_e32 v[22:23], v[6:7]
	v_mov_b64_e32 v[20:21], v[4:5]
	v_mov_b64_e32 v[18:19], v[2:3]
	v_mov_b64_e32 v[16:17], v[0:1]
	v_mov_b64_e32 v[44:45], v[12:13]
	v_mov_b64_e32 v[42:43], v[10:11]
	v_mov_b64_e32 v[40:41], v[8:9]
	v_mov_b64_e32 v[38:39], v[6:7]
	v_mov_b64_e32 v[36:37], v[4:5]
	v_mov_b64_e32 v[34:35], v[2:3]
	v_mov_b64_e32 v[32:33], v[0:1]
	v_mov_b64_e32 v[60:61], v[12:13]
	v_mov_b64_e32 v[58:59], v[10:11]
	v_mov_b64_e32 v[56:57], v[8:9]
	v_mov_b64_e32 v[54:55], v[6:7]
	v_mov_b64_e32 v[52:53], v[4:5]
	v_mov_b64_e32 v[50:51], v[2:3]
	v_mov_b64_e32 v[48:49], v[0:1]
	v_mov_b64_e32 v[76:77], v[12:13]
	v_mov_b64_e32 v[74:75], v[10:11]
	v_mov_b64_e32 v[72:73], v[8:9]
	v_mov_b64_e32 v[70:71], v[6:7]
	v_mov_b64_e32 v[68:69], v[4:5]
	v_mov_b64_e32 v[66:67], v[2:3]
	v_mov_b64_e32 v[64:65], v[0:1]
	s_waitcnt lgkmcnt(0)
	s_barrier
	s_and_b64 vcc, exec, s[0:1]
	s_cbranch_vccnz .LBB0_745
	s_add_i32 s22, s21, 3
	s_min_i32 s24, s22, s6
	s_lshl_b32 s22, s24, 6
	s_add_i32 s22, s17, s22
	s_and_b32 s24, s24, 3
	s_ashr_i32 s23, s22, 31
	s_mul_i32 s24, s24, 0x9400
	s_lshl_b64 s[22:23], s[22:23], 10
	s_add_u32 s25, s16, s22
	s_addc_u32 s26, s18, s23
	s_add_u32 s27, s19, s22
	s_addc_u32 s34, s20, s23
	s_and_b64 s[22:23], s[0:1], exec
	s_cselect_b32 s23, s26, s34
	s_cselect_b32 s22, s25, s27
	s_add_i32 s35, s24, s7
	s_mov_b32 m0, s35
	s_nop 0
	global_load_lds_dwordx4 v132, s[22:23]
	s_add_i32 s35, s24, s10
	s_addk_i32 s35, 0x400
	s_mov_b32 m0, s35
	s_nop 0
	global_load_lds_dwordx4 v131, s[22:23]
	s_and_b64 s[22:23], exec, s[8:9]
	s_cselect_b32 s23, s26, s34
	s_cselect_b32 s22, s25, s27
	s_add_i32 s35, s24, s11
	s_addk_i32 s35, 0x800
	s_mov_b32 m0, s35
	s_nop 0
	global_load_lds_dwordx4 v130, s[22:23]
	s_add_i32 s35, s24, s12
	s_addk_i32 s35, 0xc00
	s_mov_b32 m0, s35
	s_nop 0
	global_load_lds_dwordx4 v129, s[22:23]
	s_add_i32 s35, s24, s13
	s_addk_i32 s35, 0x1000
	s_mov_b32 m0, s35
	s_nop 0
	global_load_lds_dwordx4 v133, s[22:23]
	s_barrier
	s_branch .LBB0_745
; DI void attn_qk(const LAS char* kb, const bf16x8 (&qf)[4], bf16x8 (&pf)[4], float& l) {
;     f32x16 zero;
; #pragma unroll
;     for (int i = 0; i < 16; ++i) zero[i] = 0.f;
;     bf16x8 k0[4], k1[4];
; #pragma unroll
;     for (int s = 0; s < 4; ++s) k0[s] = *(const LAS bf16x8*)(kb + 32 * s);
; #pragma unroll
;     for (int s = 0; s < 4; ++s) k1[s] = *(const LAS bf16x8*)(kb + 32 * KRS + 32 * s);
;     f32x16 st0 = MFMA32(k0[0], qf[0], zero), st1 = MFMA32(k1[0], qf[0], zero);
; #pragma unroll
;     for (int s = 1; s < 4; ++s) { st0 = MFMA32(k0[s], qf[s], st0); st1 = MFMA32(k1[s], qf[s], st1); }
;     SGB(0x100, 8); SGB(0x008, 8);
;     float sum = 0.f;
; #pragma unroll
;     for (int i = 0; i < 16; ++i) { const float e = __builtin_amdgcn_exp2f(st0[i]); st0[i] = e; sum += e; }
;     pf[0] = pack8(st0, 0); pf[1] = pack8(st0, 1);
; #pragma unroll
;     for (int i = 0; i < 16; ++i) { const float e = __builtin_amdgcn_exp2f(st1[i]); st1[i] = e; sum += e; }
;     pf[2] = pack8(st1, 0); pf[3] = pack8(st1, 1);
;     l += sum;
; }
; DI void attn_pv(const LAS char* vb, const bf16x8 (&pf)[4], f32x16 (&O)[4]) {
;     s16x4 va[8], vc[8];
; #pragma unroll
;     for (int ks = 0; ks < 4; ++ks) { va[2 * ks] = vtr(vb + ks * 16 * VRS); va[2 * ks + 1] = vtr(vb + (ks * 16 + 8) * VRS); }
; #pragma unroll
;     for (int ks = 0; ks < 4; ++ks) { vc[2 * ks] = vtr(vb + ks * 16 * VRS + 64); vc[2 * ks + 1] = vtr(vb + (ks * 16 + 8) * VRS + 64); }
; #pragma unroll
;     for (int ks = 0; ks < 4; ++ks) O[0] = MFMA32(cat4(va[2 * ks], va[2 * ks + 1]), pf[ks], O[0]);
; #pragma unroll
;     for (int ks = 0; ks < 4; ++ks) { va[2 * ks] = vtr(vb + ks * 16 * VRS + 128); va[2 * ks + 1] = vtr(vb + (ks * 16 + 8) * VRS + 128); }
;     SGB(0x100, 16); SGB(0x008, 4); SGB(0x100, 8);
; #pragma unroll
;     for (int ks = 0; ks < 4; ++ks) O[1] = MFMA32(cat4(vc[2 * ks], vc[2 * ks + 1]), pf[ks], O[1]);
; #pragma unroll
;     for (int ks = 0; ks < 4; ++ks) { vc[2 * ks] = vtr(vb + ks * 16 * VRS + 192); vc[2 * ks + 1] = vtr(vb + (ks * 16 + 8) * VRS + 192); }
;     SGB(0x008, 4); SGB(0x100, 8);
; #pragma unroll
;     for (int ks = 0; ks < 4; ++ks) O[2] = MFMA32(cat4(va[2 * ks], va[2 * ks + 1]), pf[ks], O[2]);
;     SGB(0x008, 4);
; #pragma unroll
;     for (int ks = 0; ks < 4; ++ks) O[3] = MFMA32(cat4(vc[2 * ks], vc[2 * ks + 1]), pf[ks], O[3]);
;     SGB(0x008, 4);
; }
.LBB0_744:
	s_add_i32 s21, s21, 1
	s_cmp_eq_u32 s31, s21
	s_cbranch_scc1 .Lattn_exit
.LBB0_745:
	s_and_b64 vcc, exec, s[0:1]
	s_cbranch_vccz .LattnB
	s_add_i32 s22, s21, 3
	s_min_i32 s24, s22, s6
	s_lshl_b32 s22, s24, 6
	s_add_i32 s22, s17, s22
	s_and_b32 s24, s24, 3
	s_ashr_i32 s23, s22, 31
	s_mul_i32 s24, s24, 0x9400
	s_lshl_b64 s[22:23], s[22:23], 10
	s_add_u32 s25, s16, s22
	s_addc_u32 s26, s18, s23
	s_add_u32 s27, s19, s22
	s_addc_u32 s34, s20, s23
	s_cmp_gt_i32 s21, s29
	s_cbranch_scc1 .LattnA_skip
	s_and_b32 s35, s21, 3
	s_mul_i32 s35, s35, 0x9400
	v_add_u32_e32 v0, s35, v174
	v_add_u32_e32 v14, s35, v134
	ds_read_b128 v[2:5], v0
	ds_read_b128 v[6:9], v0 offset:32
	ds_read_b128 v[10:13], v0 offset:64
	ds_read_b128 v[136:139], v0 offset:96
	ds_read_b128 v[140:143], v0 offset:8704
	ds_read_b128 v[144:147], v0 offset:8736
	ds_read_b128 v[148:151], v0 offset:8768
	ds_read_b128 v[196:199], v0 offset:8800
	ds_read_b64_tr_b16 v[200:201], v14 offset:17408
	ds_read_b64_tr_b16 v[202:203], v14 offset:19968
	ds_read_b64_tr_b16 v[204:205], v14 offset:17472
	ds_read_b64_tr_b16 v[206:207], v14 offset:20032
	ds_read_b64_tr_b16 v[208:209], v14 offset:17536
	ds_read_b64_tr_b16 v[210:211], v14 offset:20096
	ds_read_b64_tr_b16 v[212:213], v14 offset:17600
	ds_read_b64_tr_b16 v[214:215], v14 offset:20160
	ds_read_b64_tr_b16 v[216:217], v14 offset:22528
	ds_read_b64_tr_b16 v[218:219], v14 offset:25088
	ds_read_b64_tr_b16 v[220:221], v14 offset:22592
	ds_read_b64_tr_b16 v[222:223], v14 offset:25152
	ds_read_b64_tr_b16 v[224:225], v14 offset:22656
	ds_read_b64_tr_b16 v[226:227], v14 offset:25216
	ds_read_b64_tr_b16 v[228:229], v14 offset:22720
	ds_read_b64_tr_b16 v[230:231], v14 offset:25280
	ds_read_b64_tr_b16 v[232:233], v14 offset:27648
	ds_read_b64_tr_b16 v[234:235], v14 offset:30208
	ds_read_b64_tr_b16 v[236:237], v14 offset:27712
	ds_read_b64_tr_b16 v[238:239], v14 offset:30272
	ds_read_b64_tr_b16 v[240:241], v14 offset:27776
	ds_read_b64_tr_b16 v[242:243], v14 offset:30336
	ds_read_b64_tr_b16 v[244:245], v14 offset:27840
	ds_read_b64_tr_b16 v[246:247], v14 offset:30400
	ds_read_b64_tr_b16 v[248:249], v14 offset:32768
	ds_read_b64_tr_b16 v[250:251], v14 offset:35328
	ds_read_b64_tr_b16 v[156:157], v14 offset:32832
	ds_read_b64_tr_b16 v[158:159], v14 offset:35392
	ds_read_b64_tr_b16 v[160:161], v14 offset:32896
	ds_read_b64_tr_b16 v[162:163], v14 offset:35456
	ds_read_b64_tr_b16 v[164:165], v14 offset:32960
	ds_read_b64_tr_b16 v[166:167], v14 offset:35520
	s_and_b64 s[22:23], s[0:1], exec
	s_cselect_b32 s23, s26, s34
	s_cselect_b32 s22, s25, s27
	s_add_i32 s35, s24, s7
	s_mov_b32 m0, s35
	s_nop 0
	global_load_lds_dwordx4 v132, s[22:23]
	s_add_i32 s35, s24, s10
	s_addk_i32 s35, 0x400
	s_mov_b32 m0, s35
	s_nop 0
	global_load_lds_dwordx4 v131, s[22:23]
	s_and_b64 s[22:23], exec, s[8:9]
	s_cselect_b32 s23, s26, s34
	s_cselect_b32 s22, s25, s27
	s_add_i32 s35, s24, s11
	s_addk_i32 s35, 0x800
	s_mov_b32 m0, s35
	s_nop 0
	global_load_lds_dwordx4 v130, s[22:23]
	s_add_i32 s35, s24, s12
	s_addk_i32 s35, 0xc00
	s_mov_b32 m0, s35
	s_nop 0
	global_load_lds_dwordx4 v129, s[22:23]
	s_add_i32 s35, s24, s13
	s_addk_i32 s35, 0x1000
	s_mov_b32 m0, s35
	s_nop 0
	global_load_lds_dwordx4 v133, s[22:23]
	s_waitcnt lgkmcnt(0)
	s_barrier
	v_mfma_f32_32x32x16_bf16 v[96:111], v[2:5], v[112:115], 0
	v_mfma_f32_32x32x16_bf16 v[96:111], v[6:9], v[116:119], v[96:111]
	v_mfma_f32_32x32x16_bf16 v[96:111], v[10:13], v[120:123], v[96:111]
	v_mfma_f32_32x32x16_bf16 v[96:111], v[136:139], v[124:127], v[96:111]
	s_nop 7
	s_nop 2
	v_mfma_f32_32x32x16_bf16 v[80:95], v[140:143], v[112:115], 0
	v_exp_f32_e32 v96, v96
	v_exp_f32_e32 v97, v97
	s_nop 0
	v_add_f32_e32 v15, v96, v97
	v_mfma_f32_32x32x16_bf16 v[80:95], v[144:147], v[116:119], v[80:95]
	v_exp_f32_e32 v98, v98
	v_exp_f32_e32 v99, v99
	v_cvt_pk_bf16_f32 v96, v96, v97
	v_add_f32_e32 v15, v98, v15
	v_mfma_f32_32x32x16_bf16 v[80:95], v[148:151], v[120:123], v[80:95]
	v_exp_f32_e32 v100, v100
	v_exp_f32_e32 v101, v101
	v_cvt_pk_bf16_f32 v97, v98, v99
	v_add_f32_e32 v15, v99, v15
	v_mfma_f32_32x32x16_bf16 v[80:95], v[196:199], v[124:127], v[80:95]
	v_exp_f32_e32 v102, v102
	v_exp_f32_e32 v103, v103
	v_cvt_pk_bf16_f32 v98, v100, v101
	v_cvt_pk_bf16_f32 v99, v102, v103
	s_nop 1
	v_mfma_f32_32x32x16_bf16 v[64:79], v[200:203], v[96:99], v[64:79]
	v_exp_f32_e32 v104, v104
	v_exp_f32_e32 v105, v105
	v_add_f32_e32 v15, v104, v15
	v_add_f32_e32 v15, v105, v15
	v_mfma_f32_32x32x16_bf16 v[48:63], v[204:207], v[96:99], v[48:63]
	v_exp_f32_e32 v106, v106
	v_exp_f32_e32 v107, v107
	v_cvt_pk_bf16_f32 v104, v104, v105
	v_add_f32_e32 v15, v106, v15
	v_mfma_f32_32x32x16_bf16 v[32:47], v[208:211], v[96:99], v[32:47]
	v_exp_f32_e32 v108, v108
	v_exp_f32_e32 v109, v109
	v_cvt_pk_bf16_f32 v105, v106, v107
	v_add_f32_e32 v15, v107, v15
	v_mfma_f32_32x32x16_bf16 v[16:31], v[212:215], v[96:99], v[16:31]
	v_exp_f32_e32 v110, v110
	v_exp_f32_e32 v111, v111
	v_cvt_pk_bf16_f32 v106, v108, v109
	v_cvt_pk_bf16_f32 v107, v110, v111
	s_nop 1
	v_mfma_f32_32x32x16_bf16 v[64:79], v[216:219], v[104:107], v[64:79]
	v_exp_f32_e32 v80, v80
	v_exp_f32_e32 v81, v81
	v_add_f32_e32 v15, v80, v15
	v_add_f32_e32 v15, v81, v15
	v_mfma_f32_32x32x16_bf16 v[48:63], v[220:223], v[104:107], v[48:63]
	v_exp_f32_e32 v82, v82
	v_exp_f32_e32 v83, v83
	v_cvt_pk_bf16_f32 v80, v80, v81
	v_add_f32_e32 v15, v82, v15
	v_mfma_f32_32x32x16_bf16 v[32:47], v[224:227], v[104:107], v[32:47]
	v_exp_f32_e32 v84, v84
	v_exp_f32_e32 v85, v85
	v_cvt_pk_bf16_f32 v81, v82, v83
	v_add_f32_e32 v15, v83, v15
	v_mfma_f32_32x32x16_bf16 v[16:31], v[228:231], v[104:107], v[16:31]
	v_exp_f32_e32 v86, v86
; #define LAS __attribute__((address_space(3)))
; DI s16x4 vtr(const LAS char* p) { return __builtin_bit_cast(s16x4, __builtin_amdgcn_ds_read_tr16_b64_v4i16((LAS v4i16_t*)p)); }
; DI bf16x8 cat4(s16x4 lo, s16x4 hi) { return __builtin_shufflevector(lo, hi, 0, 1, 2, 3, 4, 5, 6, 7); }
; #define MFMA32(a, b, c) __builtin_amdgcn_mfma_f32_32x32x16_bf16((a), (b), (c), 0, 0, 0)
; #define SGB(mask, n) __builtin_amdgcn_sched_group_barrier((mask), (n), 0)
; #define BAR_LANDED() asm volatile("s_waitcnt vmcnt(10)\n\ts_barrier" ::: "memory")
; DI void attn_pv(const LAS char* vb, const bf16x8 (&pf)[4], f32x16 (&O)[4]) {
;     s16x4 va[8], vc[8];
; #pragma unroll
;     for (int ks = 0; ks < 4; ++ks) { va[2 * ks] = vtr(vb + ks * 16 * VRS); va[2 * ks + 1] = vtr(vb + (ks * 16 + 8) * VRS); }
; #pragma unroll
;     for (int ks = 0; ks < 4; ++ks) { vc[2 * ks] = vtr(vb + ks * 16 * VRS + 64); vc[2 * ks + 1] = vtr(vb + (ks * 16 + 8) * VRS + 64); }
; #pragma unroll
;     for (int ks = 0; ks < 4; ++ks) O[0] = MFMA32(cat4(va[2 * ks], va[2 * ks + 1]), pf[ks], O[0]);
; #pragma unroll
;     for (int ks = 0; ks < 4; ++ks) { va[2 * ks] = vtr(vb + ks * 16 * VRS + 128); va[2 * ks + 1] = vtr(vb + (ks * 16 + 8) * VRS + 128); }
;     SGB(0x100, 16); SGB(0x008, 4); SGB(0x100, 8);
; #pragma unroll
;     for (int ks = 0; ks < 4; ++ks) O[1] = MFMA32(cat4(vc[2 * ks], vc[2 * ks + 1]), pf[ks], O[1]);
; #pragma unroll
;     for (int ks = 0; ks < 4; ++ks) { vc[2 * ks] = vtr(vb + ks * 16 * VRS + 192); vc[2 * ks + 1] = vtr(vb + (ks * 16 + 8) * VRS + 192); }
;     SGB(0x008, 4); SGB(0x100, 8);
; #pragma unroll
;     for (int ks = 0; ks < 4; ++ks) O[2] = MFMA32(cat4(va[2 * ks], va[2 * ks + 1]), pf[ks], O[2]);
;     SGB(0x008, 4);
; #pragma unroll
;     for (int ks = 0; ks < 4; ++ks) O[3] = MFMA32(cat4(vc[2 * ks], vc[2 * ks + 1]), pf[ks], O[3]);
;     SGB(0x008, 4);
; }
; DI void attn_unit(const Params& p, LAS unsigned char* ldsu, int kind, int b, int h, int u, float lam) {
;     ...
;         for (int t = 0; t < ntl; ++t) {
;             stage(t + 3);
;             const LAS char* sp = lds + (t & 3) * SLOT_B;
;             if (t <= my_last) { bf16x8 pf[4]; attn_qk(sp + kboff, qf, pf, l); attn_pv(sp + vboff, pf, O); }
;             BAR_LANDED();
	v_exp_f32_e32 v87, v87
	v_cvt_pk_bf16_f32 v82, v84, v85
	v_cvt_pk_bf16_f32 v83, v86, v87
	s_nop 1
	v_mfma_f32_32x32x16_bf16 v[64:79], v[232:235], v[80:83], v[64:79]
	v_exp_f32_e32 v88, v88
	v_exp_f32_e32 v89, v89
	v_add_f32_e32 v15, v88, v15
	v_add_f32_e32 v15, v89, v15
	v_mfma_f32_32x32x16_bf16 v[48:63], v[236:239], v[80:83], v[48:63]
	v_exp_f32_e32 v90, v90
	v_exp_f32_e32 v91, v91
	v_cvt_pk_bf16_f32 v88, v88, v89
	v_add_f32_e32 v15, v90, v15
	v_mfma_f32_32x32x16_bf16 v[32:47], v[240:243], v[80:83], v[32:47]
	v_exp_f32_e32 v92, v92
	v_exp_f32_e32 v93, v93
	v_cvt_pk_bf16_f32 v89, v90, v91
	v_add_f32_e32 v15, v91, v15
	v_mfma_f32_32x32x16_bf16 v[16:31], v[244:247], v[80:83], v[16:31]
	v_exp_f32_e32 v94, v94
	v_exp_f32_e32 v95, v95
	v_cvt_pk_bf16_f32 v90, v92, v93
	v_cvt_pk_bf16_f32 v91, v94, v95
	s_nop 1
	v_mfma_f32_32x32x16_bf16 v[64:79], v[248:251], v[88:91], v[64:79]
	v_add_f32_e32 v15, v100, v15
	v_add_f32_e32 v15, v101, v15
	v_add_f32_e32 v15, v102, v15
	v_add_f32_e32 v15, v103, v15
	v_mfma_f32_32x32x16_bf16 v[48:63], v[156:159], v[88:91], v[48:63]
	v_add_f32_e32 v15, v108, v15
	v_add_f32_e32 v15, v109, v15
	v_add_f32_e32 v15, v110, v15
	v_add_f32_e32 v15, v111, v15
	v_mfma_f32_32x32x16_bf16 v[32:47], v[160:163], v[88:91], v[32:47]
	v_add_f32_e32 v15, v84, v15
	v_add_f32_e32 v15, v85, v15
	v_add_f32_e32 v15, v86, v15
	v_add_f32_e32 v15, v87, v15
	v_mfma_f32_32x32x16_bf16 v[16:31], v[164:167], v[88:91], v[16:31]
	v_add_f32_e32 v15, v92, v15
	v_add_f32_e32 v15, v93, v15
	v_add_f32_e32 v15, v94, v15
	v_add_f32_e32 v15, v95, v15
	v_add_f32_e32 v175, v175, v15
	s_waitcnt vmcnt(10)
	s_barrier
	s_branch .LBB0_744
.LattnA_skip:
	s_and_b64 s[22:23], s[0:1], exec
	s_cselect_b32 s23, s26, s34
	s_cselect_b32 s22, s25, s27
	s_add_i32 s35, s24, s7
	s_mov_b32 m0, s35
	s_nop 0
	global_load_lds_dwordx4 v132, s[22:23]
	s_add_i32 s35, s24, s10
	s_addk_i32 s35, 0x400
	s_mov_b32 m0, s35
	s_nop 0
	global_load_lds_dwordx4 v131, s[22:23]
	s_and_b64 s[22:23], exec, s[8:9]
	s_cselect_b32 s23, s26, s34
	s_cselect_b32 s22, s25, s27
	s_add_i32 s35, s24, s11
	s_addk_i32 s35, 0x800
	s_mov_b32 m0, s35
	s_nop 0
	global_load_lds_dwordx4 v130, s[22:23]
	s_add_i32 s35, s24, s12
	s_addk_i32 s35, 0xc00
	s_mov_b32 m0, s35
	s_nop 0
	global_load_lds_dwordx4 v129, s[22:23]
	s_add_i32 s35, s24, s13
	s_addk_i32 s35, 0x1000
	s_mov_b32 m0, s35
	s_nop 0
	global_load_lds_dwordx4 v133, s[22:23]
	s_barrier
	s_waitcnt vmcnt(10)
	s_barrier
	s_branch .LBB0_744
.LattnB:
	s_add_i32 s22, s21, 4
	s_min_i32 s24, s22, s6
	s_lshl_b32 s22, s24, 6
	s_add_i32 s22, s17, s22
	s_and_b32 s24, s24, 3
	s_ashr_i32 s23, s22, 31
	s_mul_i32 s24, s24, 0x9400
	s_lshl_b64 s[22:23], s[22:23], 10
	s_add_u32 s25, s16, s22
	s_addc_u32 s26, s18, s23
	s_add_u32 s27, s19, s22
	s_addc_u32 s34, s20, s23
	s_cmp_gt_i32 s21, s29
	s_cbranch_scc1 .LattnB_skip
	s_and_b32 s35, s21, 3
	s_mul_i32 s35, s35, 0x9400
	v_add_u32_e32 v0, s35, v174
	v_add_u32_e32 v14, s35, v134
	ds_read_b128 v[2:5], v0
	ds_read_b128 v[6:9], v0 offset:32
	ds_read_b128 v[10:13], v0 offset:64
	ds_read_b128 v[136:139], v0 offset:96
	ds_read_b128 v[140:143], v0 offset:8704
	ds_read_b128 v[144:147], v0 offset:8736
	ds_read_b128 v[148:151], v0 offset:8768
	ds_read_b128 v[196:199], v0 offset:8800
	ds_read_b64_tr_b16 v[200:201], v14 offset:17408
	ds_read_b64_tr_b16 v[202:203], v14 offset:19968
	ds_read_b64_tr_b16 v[204:205], v14 offset:17472
	ds_read_b64_tr_b16 v[206:207], v14 offset:20032
	ds_read_b64_tr_b16 v[208:209], v14 offset:17536
	ds_read_b64_tr_b16 v[210:211], v14 offset:20096
	ds_read_b64_tr_b16 v[212:213], v14 offset:17600
	ds_read_b64_tr_b16 v[214:215], v14 offset:20160
	ds_read_b64_tr_b16 v[216:217], v14 offset:22528
	ds_read_b64_tr_b16 v[218:219], v14 offset:25088
	ds_read_b64_tr_b16 v[220:221], v14 offset:22592
	ds_read_b64_tr_b16 v[222:223], v14 offset:25152
	ds_read_b64_tr_b16 v[224:225], v14 offset:22656
	ds_read_b64_tr_b16 v[226:227], v14 offset:25216
	ds_read_b64_tr_b16 v[228:229], v14 offset:22720
	ds_read_b64_tr_b16 v[230:231], v14 offset:25280
	ds_read_b64_tr_b16 v[232:233], v14 offset:27648
	ds_read_b64_tr_b16 v[234:235], v14 offset:30208
	ds_read_b64_tr_b16 v[236:237], v14 offset:27712
	ds_read_b64_tr_b16 v[238:239], v14 offset:30272
	ds_read_b64_tr_b16 v[240:241], v14 offset:27776
	ds_read_b64_tr_b16 v[242:243], v14 offset:30336
	ds_read_b64_tr_b16 v[244:245], v14 offset:27840
	ds_read_b64_tr_b16 v[246:247], v14 offset:30400
	ds_read_b64_tr_b16 v[248:249], v14 offset:32768
	ds_read_b64_tr_b16 v[250:251], v14 offset:35328
	ds_read_b64_tr_b16 v[156:157], v14 offset:32832
	ds_read_b64_tr_b16 v[158:159], v14 offset:35392
	ds_read_b64_tr_b16 v[160:161], v14 offset:32896
	ds_read_b64_tr_b16 v[162:163], v14 offset:35456
	ds_read_b64_tr_b16 v[164:165], v14 offset:32960
	ds_read_b64_tr_b16 v[166:167], v14 offset:35520
	s_waitcnt vmcnt(10)
	s_waitcnt lgkmcnt(0)
	s_barrier
; DI void attn_qk(const LAS char* kb, const bf16x8 (&qf)[4], bf16x8 (&pf)[4], float& l) {
;     f32x16 zero;
; #pragma unroll
;     for (int i = 0; i < 16; ++i) zero[i] = 0.f;
;     bf16x8 k0[4], k1[4];
; #pragma unroll
;     for (int s = 0; s < 4; ++s) k0[s] = *(const LAS bf16x8*)(kb + 32 * s);
; #pragma unroll
;     for (int s = 0; s < 4; ++s) k1[s] = *(const LAS bf16x8*)(kb + 32 * KRS + 32 * s);
;     f32x16 st0 = MFMA32(k0[0], qf[0], zero), st1 = MFMA32(k1[0], qf[0], zero);
; #pragma unroll
;     for (int s = 1; s < 4; ++s) { st0 = MFMA32(k0[s], qf[s], st0); st1 = MFMA32(k1[s], qf[s], st1); }
;     SGB(0x100, 8); SGB(0x008, 8);
;     float sum = 0.f;
; #pragma unroll
;     for (int i = 0; i < 16; ++i) { const float e = __builtin_amdgcn_exp2f(st0[i]); st0[i] = e; sum += e; }
;     pf[0] = pack8(st0, 0); pf[1] = pack8(st0, 1);
; #pragma unroll
;     for (int i = 0; i < 16; ++i) { const float e = __builtin_amdgcn_exp2f(st1[i]); st1[i] = e; sum += e; }
;     pf[2] = pack8(st1, 0); pf[3] = pack8(st1, 1);
;     l += sum;
; }
; DI void attn_pv(const LAS char* vb, const bf16x8 (&pf)[4], f32x16 (&O)[4]) {
;     s16x4 va[8], vc[8];
; #pragma unroll
;     for (int ks = 0; ks < 4; ++ks) { va[2 * ks] = vtr(vb + ks * 16 * VRS); va[2 * ks + 1] = vtr(vb + (ks * 16 + 8) * VRS); }
; #pragma unroll
;     for (int ks = 0; ks < 4; ++ks) { vc[2 * ks] = vtr(vb + ks * 16 * VRS + 64); vc[2 * ks + 1] = vtr(vb + (ks * 16 + 8) * VRS + 64); }
; #pragma unroll
;     for (int ks = 0; ks < 4; ++ks) O[0] = MFMA32(cat4(va[2 * ks], va[2 * ks + 1]), pf[ks], O[0]);
; #pragma unroll
;     for (int ks = 0; ks < 4; ++ks) { va[2 * ks] = vtr(vb + ks * 16 * VRS + 128); va[2 * ks + 1] = vtr(vb + (ks * 16 + 8) * VRS + 128); }
;     SGB(0x100, 16); SGB(0x008, 4); SGB(0x100, 8);
; #pragma unroll
;     for (int ks = 0; ks < 4; ++ks) O[1] = MFMA32(cat4(vc[2 * ks], vc[2 * ks + 1]), pf[ks], O[1]);
; #pragma unroll
;     for (int ks = 0; ks < 4; ++ks) { vc[2 * ks] = vtr(vb + ks * 16 * VRS + 192); vc[2 * ks + 1] = vtr(vb + (ks * 16 + 8) * VRS + 192); }
;     SGB(0x008, 4); SGB(0x100, 8);
; #pragma unroll
;     for (int ks = 0; ks < 4; ++ks) O[2] = MFMA32(cat4(va[2 * ks], va[2 * ks + 1]), pf[ks], O[2]);
;     SGB(0x008, 4);
; #pragma unroll
;     for (int ks = 0; ks < 4; ++ks) O[3] = MFMA32(cat4(vc[2 * ks], vc[2 * ks + 1]), pf[ks], O[3]);
;     SGB(0x008, 4);
; }
	v_mfma_f32_32x32x16_bf16 v[96:111], v[2:5], v[112:115], 0
	v_mfma_f32_32x32x16_bf16 v[96:111], v[6:9], v[116:119], v[96:111]
	v_mfma_f32_32x32x16_bf16 v[96:111], v[10:13], v[120:123], v[96:111]
	v_mfma_f32_32x32x16_bf16 v[96:111], v[136:139], v[124:127], v[96:111]
	s_nop 7
	s_nop 2
	v_mfma_f32_32x32x16_bf16 v[80:95], v[140:143], v[112:115], 0
	v_exp_f32_e32 v96, v96
	v_exp_f32_e32 v97, v97
	s_nop 0
	v_add_f32_e32 v15, v96, v97
	v_mfma_f32_32x32x16_bf16 v[80:95], v[144:147], v[116:119], v[80:95]
	v_exp_f32_e32 v98, v98
	v_exp_f32_e32 v99, v99
	v_cvt_pk_bf16_f32 v96, v96, v97
	v_add_f32_e32 v15, v98, v15
	v_mfma_f32_32x32x16_bf16 v[80:95], v[148:151], v[120:123], v[80:95]
	v_exp_f32_e32 v100, v100
	v_exp_f32_e32 v101, v101
	v_cvt_pk_bf16_f32 v97, v98, v99
	v_add_f32_e32 v15, v99, v15
	v_mfma_f32_32x32x16_bf16 v[80:95], v[196:199], v[124:127], v[80:95]
	v_exp_f32_e32 v102, v102
	v_exp_f32_e32 v103, v103
	v_cvt_pk_bf16_f32 v98, v100, v101
	v_cvt_pk_bf16_f32 v99, v102, v103
	s_nop 1
	v_mfma_f32_32x32x16_bf16 v[64:79], v[200:203], v[96:99], v[64:79]
	v_exp_f32_e32 v104, v104
	v_exp_f32_e32 v105, v105
	v_add_f32_e32 v15, v104, v15
	v_add_f32_e32 v15, v105, v15
	v_mfma_f32_32x32x16_bf16 v[48:63], v[204:207], v[96:99], v[48:63]
	v_exp_f32_e32 v106, v106
	v_exp_f32_e32 v107, v107
	v_cvt_pk_bf16_f32 v104, v104, v105
	v_add_f32_e32 v15, v106, v15
	v_mfma_f32_32x32x16_bf16 v[32:47], v[208:211], v[96:99], v[32:47]
	v_exp_f32_e32 v108, v108
	v_exp_f32_e32 v109, v109
	v_cvt_pk_bf16_f32 v105, v106, v107
	v_add_f32_e32 v15, v107, v15
	v_mfma_f32_32x32x16_bf16 v[16:31], v[212:215], v[96:99], v[16:31]
	v_exp_f32_e32 v110, v110
	v_exp_f32_e32 v111, v111
	v_cvt_pk_bf16_f32 v106, v108, v109
	v_cvt_pk_bf16_f32 v107, v110, v111
	s_nop 1
	v_mfma_f32_32x32x16_bf16 v[64:79], v[216:219], v[104:107], v[64:79]
	v_exp_f32_e32 v80, v80
	v_exp_f32_e32 v81, v81
	v_add_f32_e32 v15, v80, v15
	v_add_f32_e32 v15, v81, v15
	s_and_b64 s[22:23], s[0:1], exec
	s_cselect_b32 s23, s26, s34
	s_cselect_b32 s22, s25, s27
	s_add_i32 s35, s24, s7
	s_mov_b32 m0, s35
	s_nop 0
	global_load_lds_dwordx4 v132, s[22:23]
	v_mfma_f32_32x32x16_bf16 v[48:63], v[220:223], v[104:107], v[48:63]
	v_exp_f32_e32 v82, v82
	v_exp_f32_e32 v83, v83
	v_cvt_pk_bf16_f32 v80, v80, v81
	v_add_f32_e32 v15, v82, v15
	v_mfma_f32_32x32x16_bf16 v[32:47], v[224:227], v[104:107], v[32:47]
	v_exp_f32_e32 v84, v84
	v_exp_f32_e32 v85, v85
	v_cvt_pk_bf16_f32 v81, v82, v83
	v_add_f32_e32 v15, v83, v15
	s_add_i32 s35, s24, s10
	s_addk_i32 s35, 0x400
	s_mov_b32 m0, s35
	s_nop 0
	global_load_lds_dwordx4 v131, s[22:23]
	v_mfma_f32_32x32x16_bf16 v[16:31], v[228:231], v[104:107], v[16:31]
	v_exp_f32_e32 v86, v86
	v_exp_f32_e32 v87, v87
	v_cvt_pk_bf16_f32 v82, v84, v85
	v_cvt_pk_bf16_f32 v83, v86, v87
	s_nop 1
	v_mfma_f32_32x32x16_bf16 v[64:79], v[232:235], v[80:83], v[64:79]
	v_exp_f32_e32 v88, v88
	v_exp_f32_e32 v89, v89
	v_add_f32_e32 v15, v88, v15
	v_add_f32_e32 v15, v89, v15
	s_and_b64 s[22:23], exec, s[8:9]
	s_cselect_b32 s23, s26, s34
	s_cselect_b32 s22, s25, s27
	s_add_i32 s35, s24, s11
	s_addk_i32 s35, 0x800
	s_mov_b32 m0, s35
	s_nop 0
	global_load_lds_dwordx4 v130, s[22:23]
	v_mfma_f32_32x32x16_bf16 v[48:63], v[236:239], v[80:83], v[48:63]
	v_exp_f32_e32 v90, v90
	v_exp_f32_e32 v91, v91
	v_cvt_pk_bf16_f32 v88, v88, v89
	v_add_f32_e32 v15, v90, v15
	v_mfma_f32_32x32x16_bf16 v[32:47], v[240:243], v[80:83], v[32:47]
	v_exp_f32_e32 v92, v92
	v_exp_f32_e32 v93, v93
	v_cvt_pk_bf16_f32 v89, v90, v91
	v_add_f32_e32 v15, v91, v15
	s_add_i32 s35, s24, s12
	s_addk_i32 s35, 0xc00
	s_mov_b32 m0, s35
	s_nop 0
	global_load_lds_dwordx4 v129, s[22:23]
	v_mfma_f32_32x32x16_bf16 v[16:31], v[244:247], v[80:83], v[16:31]
	v_exp_f32_e32 v94, v94
	v_exp_f32_e32 v95, v95
	v_cvt_pk_bf16_f32 v90, v92, v93
	v_cvt_pk_bf16_f32 v91, v94, v95
	s_nop 1
	v_mfma_f32_32x32x16_bf16 v[64:79], v[248:251], v[88:91], v[64:79]
	v_add_f32_e32 v15, v100, v15
	v_add_f32_e32 v15, v101, v15
	v_add_f32_e32 v15, v102, v15
	v_add_f32_e32 v15, v103, v15
	s_add_i32 s35, s24, s13
	s_addk_i32 s35, 0x1000
	s_mov_b32 m0, s35
	s_nop 0
	global_load_lds_dwordx4 v133, s[22:23]
	v_mfma_f32_32x32x16_bf16 v[48:63], v[156:159], v[88:91], v[48:63]
	v_add_f32_e32 v15, v108, v15
	v_add_f32_e32 v15, v109, v15
	v_add_f32_e32 v15, v110, v15
	v_add_f32_e32 v15, v111, v15
	v_mfma_f32_32x32x16_bf16 v[32:47], v[160:163], v[88:91], v[32:47]
	v_add_f32_e32 v15, v84, v15
	v_add_f32_e32 v15, v85, v15
	v_add_f32_e32 v15, v86, v15
	v_add_f32_e32 v15, v87, v15
	v_mfma_f32_32x32x16_bf16 v[16:31], v[164:167], v[88:91], v[16:31]
	v_add_f32_e32 v15, v92, v15
	v_add_f32_e32 v15, v93, v15
	v_add_f32_e32 v15, v94, v15
	v_add_f32_e32 v15, v95, v15
	v_add_f32_e32 v175, v175, v15
	s_barrier
	s_branch .LBB0_744
.LattnB_skip:
	s_waitcnt vmcnt(10)
	s_barrier
	s_and_b64 s[22:23], s[0:1], exec
	s_cselect_b32 s23, s26, s34
	s_cselect_b32 s22, s25, s27
	s_add_i32 s35, s24, s7
	s_mov_b32 m0, s35
	s_nop 0
	global_load_lds_dwordx4 v132, s[22:23]
	s_add_i32 s35, s24, s10
	s_addk_i32 s35, 0x400
	s_mov_b32 m0, s35
	s_nop 0
	global_load_lds_dwordx4 v131, s[22:23]
	s_and_b64 s[22:23], exec, s[8:9]
	s_cselect_b32 s23, s26, s34
	s_cselect_b32 s22, s25, s27
	s_add_i32 s35, s24, s11
	s_addk_i32 s35, 0x800
	s_mov_b32 m0, s35
	s_nop 0
	global_load_lds_dwordx4 v130, s[22:23]
	s_add_i32 s35, s24, s12
	s_addk_i32 s35, 0xc00
	s_mov_b32 m0, s35
	s_nop 0
	global_load_lds_dwordx4 v129, s[22:23]
	s_add_i32 s35, s24, s13
	s_addk_i32 s35, 0x1000
	s_mov_b32 m0, s35
	s_nop 0
	global_load_lds_dwordx4 v133, s[22:23]
	s_barrier
	s_branch .LBB0_744
.Lattn_exit:
	s_and_b64 vcc, exec, s[0:1]
	s_cbranch_vccz .LBB0_747
	s_barrier
	s_branch .LBB0_747
